# adds: XS (bf16 A operand) stored as [column half][16 rows][64 B] blocks: OUT/DOWN epilogue XS stores and IN A-operand DMA become contiguous 1 KiB accesses; UP half step 512 to 256 B
# speedup vs baseline: 1.0146x; 1.0004x over previous
; __device__ __forceinline__ unsigned cvt_pk_bf16_c(float lo, float hi) { const f32x2_t v = {lo, hi}; return __builtin_bit_cast(unsigned, __builtin_convertvector(v, bf16x2_t)); }
; __device__ __forceinline__ float bperm(float v, int src_lane) { return __int_as_float(__builtin_amdgcn_ds_bpermute(src_lane << 2, __float_as_int(v))); }
; __host__ __device__ __forceinline__ size_t xs_off(int row, int col) { return (size_t)(row >> 8) * (256 * D) + (size_t)(col >> 6) * (256 * 64) + (size_t)((row & 255) * 64 + (col & 63)); }
; __device__ __forceinline__ void pro_c(LAS unsigned char* lds, const float* const* in, unsigned char* wsl, int cid, int G, int tid) {
;     ...
;     for (int row = cid * 8 + wave; row < M; row += G * 8) { const int b = row / SEQ;
;         const float* xr = in[0] + (size_t)row * D; bf16_t* xs = (bf16_t*)(wsl + O_XS); float* rss = (float*)(wsl + O_RSS1) + (size_t)row * 32;
; #pragma unroll
;         for (int j = 0; j < 8; ++j) { const int c = 4 * lane + 256 * j; const f32x4 v = __builtin_nontemporal_load((const f32x4*)(xr + c));
;             const f32x4 g = *(const f32x4*)(in[4] + c), sc = *(const f32x4*)(MOD + (size_t)b * 6 * D + D + c);
;             u32x2 o; o.x = cvt_pk_bf16_c(v.x * (g.x * (1.f + sc.x)), v.y * (g.y * (1.f + sc.y))); o.y = cvt_pk_bf16_c(v.z * (g.z * (1.f + sc.z)), v.w * (g.w * (1.f + sc.w)));
;             *(u32x2*)(xs + xs_off(row, c)) = o;
;             float ss = (v.x * v.x + v.y * v.y) + (v.z * v.z + v.w * v.w);
;             ss += bperm(ss, lane ^ 1); ss += bperm(ss, lane ^ 2); ss += bperm(ss, lane ^ 4); ss += bperm(ss, lane ^ 8);
;             if ((lane & 15) == 0) rss[4 * j + (lane >> 4)] = ss; }
.LBB0_234:
	v_readlane_b32 s12, v254, 30
	s_cmpk_gt_i32 s6, 0x3fff
	v_readlane_b32 s13, v254, 31
	v_readlane_b32 s20, v254, 38
	v_readlane_b32 s21, v254, 39
	v_readlane_b32 s40, v254, 14
	s_mov_b32 s63, s74
	v_readlane_b32 s14, v254, 32
	v_readlane_b32 s15, v254, 33
	v_readlane_b32 s16, v254, 34
	v_readlane_b32 s17, v254, 35
	v_readlane_b32 s18, v254, 36
	v_readlane_b32 s19, v254, 37
	v_readlane_b32 s22, v254, 40
	v_readlane_b32 s23, v254, 41
	v_readlane_b32 s24, v254, 42
	v_readlane_b32 s25, v254, 43
	v_readlane_b32 s26, v254, 44
	v_readlane_b32 s27, v254, 45
	v_readlane_b32 s41, v254, 15
	v_readlane_b32 s42, v254, 16
	v_readlane_b32 s43, v254, 17
	v_readlane_b32 s44, v254, 18
	v_readlane_b32 s45, v254, 19
	v_readlane_b32 s46, v254, 20
	v_readlane_b32 s47, v254, 21
	v_readlane_b32 s48, v254, 22
	v_readlane_b32 s49, v254, 23
	v_readlane_b32 s50, v254, 24
	v_readlane_b32 s51, v254, 25
	v_readlane_b32 s52, v254, 26
	v_readlane_b32 s53, v254, 27
	v_readlane_b32 s54, v254, 28
	v_readlane_b32 s55, v254, 29
	s_cbranch_scc1 .LBB0_253
	v_and_b32_e32 v0, 15, v53
	v_cmp_eq_u32_e32 vcc, 0, v0
	v_lshlrev_b32_e32 v0, 10, v55
	v_or_b32_e32 v18, 0x100, v52
	v_and_b32_e32 v16, 0xc000, v0
	v_lshlrev_b32_e32 v0, 8, v18
	v_or_b32_e32 v22, 0x200, v52
	v_and_b32_e32 v20, 0x1c000, v0
	v_lshlrev_b32_e32 v0, 8, v22
	v_or_b32_e32 v26, 0x300, v52
	v_and_b32_e32 v24, 0x2c000, v0
	v_lshlrev_b32_e32 v0, 8, v26
	v_or_b32_e32 v30, 0x400, v52
	s_add_u32 s3, s3, 0x20104000
	v_and_b32_e32 v28, 0x3c000, v0
	v_lshlrev_b32_e32 v0, 8, v30
	v_or_b32_e32 v44, 0x500, v52
	s_addc_u32 s16, s33, 0
	v_and_b32_e32 v32, 0x4c000, v0
	v_lshlrev_b32_e32 v0, 8, v44
	v_or_b32_e32 v48, 0x600, v52
	s_lshl_b32 s1, s7, 6
	s_ashr_i32 s7, s6, 31
	s_lshl_b32 s0, s38, 3
	v_and_b32_e32 v46, 0x5c000, v0
	v_lshlrev_b32_e32 v0, 8, v48
	v_or_b32_e32 v54, 0x700, v52
	s_add_i32 s2, s2, s1
	s_lshl_b32 s17, s38, 9
	s_lshl_b64 s[10:11], s[6:7], 13
	v_and_b32_e32 v50, 0x6c000, v0
	v_lshlrev_b32_e32 v0, 8, v54
	s_add_u32 s10, s12, s10
	s_waitcnt lgkmcnt(0)
	v_mov_b32_e32 v1, 0
	v_and_b32_e32 v56, 0x7c000, v0
	v_lshlrev_b32_e32 v0, 4, v55
	s_addc_u32 s11, s13, s11
	v_lshl_add_u64 v[12:13], s[10:11], 0, v[0:1]
	s_mov_b64 s[10:11], 0x1000
	s_ashr_i32 s1, s0, 31
	v_lshlrev_b32_e32 v4, 2, v30
	v_mov_b32_e32 v5, v1
	v_lshlrev_b32_e32 v6, 2, v44
	v_mov_b32_e32 v7, v1
	v_lshlrev_b32_e32 v8, 2, v48
	v_mov_b32_e32 v9, v1
	v_lshlrev_b32_e32 v10, 2, v54
	v_mov_b32_e32 v11, v1
	v_lshl_add_u64 v[12:13], v[12:13], 0, s[10:11]
	s_lshl_b64 s[10:11], s[0:1], 13
	s_lshl_b64 s[12:13], s[6:7], 7
	v_lshl_add_u64 v[2:3], s[20:21], 0, v[0:1]
	v_lshl_add_u64 v[4:5], s[20:21], 0, v[4:5]
	v_lshl_add_u64 v[6:7], s[20:21], 0, v[6:7]
	v_lshl_add_u64 v[8:9], s[20:21], 0, v[8:9]
	v_lshl_add_u64 v[10:11], s[20:21], 0, v[10:11]
	s_add_u32 s7, s8, s12
	v_readlane_b32 s20, v254, 0
	s_addc_u32 s9, s9, s13
	v_readlane_b32 s24, v254, 4
	v_lshrrev_b32_e32 v0, 2, v55
	v_readlane_b32 s25, v254, 5
	s_add_u32 s8, s24, s7
	v_and_b32_e32 v0, 12, v0
	s_addc_u32 s9, s25, s9
	v_lshl_add_u64 v[14:15], s[8:9], 0, v[0:1]
	s_mov_b64 s[8:9], 0x304040
	v_and_b32_e32 v34, 28, v52
	v_and_b32_e32 v62, 32, v52
	v_lshl_or_b32 v34, v62, 4, v34
	v_xor_b32_e32 v35, 4, v52
	v_xor_b32_e32 v36, 8, v52
	v_xor_b32_e32 v37, 16, v52
	v_xor_b32_e32 v38, 32, v52
	v_lshl_add_u64 v[14:15], v[14:15], 0, s[8:9]
	s_lshl_b64 s[8:9], s[0:1], 7
	v_lshlrev_b32_e32 v39, 2, v52
	v_lshlrev_b32_e32 v16, 1, v16
	v_lshlrev_b32_e32 v40, 2, v18
	v_lshlrev_b32_e32 v18, 1, v20
	v_lshlrev_b32_e32 v41, 2, v22
	v_lshlrev_b32_e32 v20, 1, v24
	v_lshlrev_b32_e32 v42, 2, v26
	v_lshlrev_b32_e32 v22, 1, v28
	v_lshlrev_b32_e32 v43, 2, v30
	v_lshlrev_b32_e32 v24, 1, v32
	v_lshlrev_b32_e32 v44, 2, v44
	v_lshlrev_b32_e32 v26, 1, v46
	v_lshlrev_b32_e32 v45, 2, v48
	v_lshlrev_b32_e32 v28, 1, v50
	v_lshlrev_b32_e32 v46, 2, v54
	v_lshlrev_b32_e32 v30, 1, v56
	v_mov_b32_e32 v17, v1
	v_readlane_b32 s21, v254, 1
	v_readlane_b32 s22, v254, 2
	v_readlane_b32 s23, v254, 3
	v_readlane_b32 s26, v254, 6
	v_readlane_b32 s27, v254, 7
	s_branch .LBB0_237

; __device__ __forceinline__ unsigned cvt_pk_bf16_c(float lo, float hi) { const f32x2_t v = {lo, hi}; return __builtin_bit_cast(unsigned, __builtin_convertvector(v, bf16x2_t)); }
; __device__ __forceinline__ float bperm(float v, int src_lane) { return __int_as_float(__builtin_amdgcn_ds_bpermute(src_lane << 2, __float_as_int(v))); }
; __host__ __device__ __forceinline__ size_t xs_off(int row, int col) { return (size_t)(row >> 8) * (256 * D) + (size_t)(col >> 6) * (256 * 64) + (size_t)((row & 255) * 64 + (col & 63)); }
; __device__ __forceinline__ void pro_c(LAS unsigned char* lds, const float* const* in, unsigned char* wsl, int cid, int G, int tid) {
;     ...
;         for (int j = 0; j < 8; ++j) { const int c = 4 * lane + 256 * j; const f32x4 v = __builtin_nontemporal_load((const f32x4*)(xr + c));
;             const f32x4 g = *(const f32x4*)(in[4] + c), sc = *(const f32x4*)(MOD + (size_t)b * 6 * D + D + c);
;             u32x2 o; o.x = cvt_pk_bf16_c(v.x * (g.x * (1.f + sc.x)), v.y * (g.y * (1.f + sc.y))); o.y = cvt_pk_bf16_c(v.z * (g.z * (1.f + sc.z)), v.w * (g.w * (1.f + sc.w)));
;             *(u32x2*)(xs + xs_off(row, c)) = o;
;             float ss = (v.x * v.x + v.y * v.y) + (v.z * v.z + v.w * v.w);
;             ss += bperm(ss, lane ^ 1); ss += bperm(ss, lane ^ 2); ss += bperm(ss, lane ^ 4); ss += bperm(ss, lane ^ 8);
;             if ((lane & 15) == 0) rss[4 * j + (lane >> 4)] = ss; }
.LBB0_237:
	global_load_dwordx4 v[48:51], v[12:13], off offset:-4096 nt
	s_ashr_i32 s1, s6, 31
	s_lshr_b32 s1, s1, 20
	s_add_i32 s1, s6, s1
	s_ashr_i32 s1, s1, 12
	s_mul_i32 s12, s1, 6
	s_ashr_i32 s13, s12, 31
	s_lshl_b64 s[12:13], s[12:13], 13
	s_add_u32 s1, s4, s12
	s_addc_u32 s7, s5, s13
	s_add_u32 s12, s1, 0x2000
	s_addc_u32 s13, s7, 0
	global_load_dwordx4 v[52:55], v39, s[12:13]
	global_load_dwordx4 v[56:59], v[2:3], off
	s_ashr_i32 s14, s6, 8
	s_ashr_i32 s15, s14, 31
	s_and_b32 s1, s2, 0x3fc0
	s_and_b32 s100, s1, 0x3c0
	s_lshr_b32 s100, s100, 1
	s_and_b32 s1, s1, 0x3c00
	s_or_b32 s1, s1, s100
	s_lshl_b64 s[14:15], s[14:15], 20
	v_or_b32_e32 v21, s1, v34
	s_add_u32 s14, s3, s14
	s_addc_u32 s15, s16, s15
	s_waitcnt vmcnt(2)
	v_mul_f32_e32 v0, v49, v49
	s_waitcnt lgkmcnt(0)
	v_mul_f32_e32 v19, v51, v51
	v_fmac_f32_e32 v0, v48, v48
	v_fmac_f32_e32 v19, v50, v50
	v_add_f32_e32 v0, v0, v19
	ds_bpermute_b32 v19, v35, v0
	s_waitcnt lgkmcnt(0)
	v_add_f32_e32 v19, v0, v19
	ds_bpermute_b32 v23, v36, v19
	v_lshlrev_b32_e32 v0, 1, v21
	v_lshl_add_u64 v[32:33], s[14:15], 0, v[0:1]
	s_waitcnt vmcnt(1)
	v_pk_add_f32 v[52:53], v[52:53], 1.0 op_sel_hi:[1,0]
	s_waitcnt lgkmcnt(0)
	v_add_f32_e32 v0, v19, v23
	ds_bpermute_b32 v19, v37, v0
	s_waitcnt vmcnt(0)
	v_pk_mul_f32 v[52:53], v[56:57], v[52:53]
	s_waitcnt lgkmcnt(0)
	v_add_f32_e32 v0, v0, v19
	ds_bpermute_b32 v19, v38, v0
	v_pk_mul_f32 v[48:49], v[48:49], v[52:53]
	v_pk_add_f32 v[52:53], v[54:55], 1.0 op_sel_hi:[1,0]
	v_cvt_pk_bf16_f32 v48, v48, v49
	v_pk_mul_f32 v[52:53], v[58:59], v[52:53]
	s_nop 0
	v_pk_mul_f32 v[50:51], v[50:51], v[52:53]
	s_nop 0
	v_cvt_pk_bf16_f32 v49, v50, v51
	v_lshl_add_u64 v[50:51], v[32:33], 0, v[16:17]
	global_store_dwordx2 v[50:51], v[48:49], off
	s_and_saveexec_b64 s[14:15], vcc
	s_cbranch_execz .LBB0_239
	s_waitcnt lgkmcnt(0)
	v_add_f32_e32 v0, v0, v19
	global_store_dword v[14:15], v0, off offset:-64

; #define LAS __attribute__((address_space(3)))
; #define PHASE_OPAQUE() size_t zoff_ = 0; int cid = (int)blockIdx.x; asm volatile("" : "+s"(zoff_), "+s"(cid)); unsigned char* wsl = ws + zoff_; const int tid = MK_TID()
;     ...
;     constexpr ptrdiff_t kstep0 = KSB ? (ptrdiff_t)KSB : (ptrdiff_t)(BK * 2), kstepA0 = KSA ? (ptrdiff_t)KSA : (ptrdiff_t)(BK * 2), kstep = KREV ? -kstep0 : kstep0, kstepA = KREV ? -kstepA0 : kstepA0;
;     constexpr ptrdiff_t kofB = KREV ? (ptrdiff_t)(KK / BK - 1) * kstep0 : 0, kofA = KREV ? (ptrdiff_t)(KK / BK - 1) * kstepA0 : 0;
;     constexpr size_t hstepA = (size_t)(ROWP ? 4 : HALF) * LDA * 2, hstepB = (size_t)HALF * LDB * 2;
;     constexpr size_t tstepA = TSA ? (size_t)TSA : (size_t)2 * HALF * LDA * 2, tstepB = TSB ? (size_t)TSB : 2 * hstepB;
;     const unsigned ldsw = (unsigned)wid * 1024u;
; __global__ void __launch_bounds__(NTHR, 2) mk_fwd(MKArgs args) {
;     ...
;         if (IN(base + LP_UP)) {
;             PHASE_OPAQUE();
;             pg8::Gemm g{(const bf16_t*)(wsl + O_XS), (const bf16_t*)(wsl + O_WTUP) + (size_t)l * NUP * D}; pg8::StaticOrder S; S.init(M, NUP, G, cid);
;             const FillRstd<pg8::StaticOrder> FR{lds, (const float*)(wsl + O_RSS2), &S, tid};
;             EpiUp E{(const LAS float*)(lds + RSTD_OFF), (const float*)(wsl + O_SW2) + (size_t)l * NB * NUP, args.in[13] + (size_t)l * 3 * DFF, args.in[14] + (size_t)l * DFF, (bf16_t*)(wsl + O_ACT), (float*)(wsl + O_HA), (float*)(wsl + O_HV)};
;             pg8::gemm_phase<EpiUp, pg8::StaticOrder, 64, 64, D, 0, PG8_ALIGN, PG8_SP2, true, FillRstd<pg8::StaticOrder>, 256 * 64 * 2, (long)256 * D * 2, false, 256 * 64 * 2, (long)256 * D * 2>(lds, g, S, E, tid, FR);
.LBB0_304:
	s_and_b32 s2, s38, 7
	s_cmp_eq_u32 s2, 0
	s_cselect_b64 s[2:3], -1, 0
	s_ashr_i32 s4, s38, 3
	s_lshl_b32 s6, s38, 2
	v_writelane_b32 v254, s4, 47
	s_and_b64 s[4:5], s[0:1], exec
	s_cselect_b32 s93, 4, s6
	s_lshl_b32 s94, s38, 8
	s_lshl_b32 s95, s38, 1
	s_ashr_i32 s39, s38, 31
	s_movk_i32 s6, 0x5800
	s_and_b64 s[4:5], s[0:1], exec
	s_cselect_b32 s56, s6, 0x2c000
	s_lshl_b32 s6, s38, 9
	s_and_b64 s[4:5], s[0:1], exec
	s_cselect_b32 s57, 0x4000, s6
	s_lshl_b64 s[4:5], s[38:39], 1
	v_writelane_b32 v254, s4, 48
	s_waitcnt vmcnt(0)
	v_cndmask_b32_e64 v0, 0, 1, s[2:3]
	v_cmp_ne_u32_e64 s[2:3], 1, v0
	v_writelane_b32 v254, s5, 49
	s_mov_b32 s45, 0
	v_writelane_b32 v254, s2, 50
	s_movk_i32 s60, 0x4000
	s_movk_i32 s65, 0x2000
	v_writelane_b32 v254, s3, 51
	s_add_i32 s2, 0, 0x20400
	v_writelane_b32 v254, s2, 52
	s_add_i32 s2, 0, 0x27f30
	s_mov_b32 s3, 0x800000
	v_writelane_b32 v254, s2, 53
	s_mov_b32 s2, s70
	v_writelane_b32 v254, s2, 54
	s_mov_b32 s66, 0x10000
	s_waitcnt lgkmcnt(0)
	v_mov_b32_e32 v1, 0
	v_writelane_b32 v254, s3, 55
	v_writelane_b32 v254, s63, 56
	v_writelane_b32 v254, s93, 57
	v_writelane_b32 v254, s94, 58
	v_writelane_b32 v254, s95, 59
	v_writelane_b32 v254, s56, 60
	v_writelane_b32 v254, s57, 61
	v_writelane_b32 v254, s42, 62
	s_movk_i32 s71, 0x6000
	v_mov_b32_e32 v240, 0x358637bd
	s_movk_i32 s82, 0x5000
	s_mov_b32 s4, 0x3f317217
	s_mov_b32 s5, 0x7f800000
	s_mov_b32 s50, 0x3db504f3
	s_mov_b64 s[52:53], 0x80
	s_movk_i32 s62, 0x210
	s_movk_i32 s84, 0x80
	s_movk_i32 s92, 0x1080
	v_mov_b32_e32 v241, 1
	s_movk_i32 s80, 0x3000
	s_movk_i32 s81, 0x7000
	v_mov_b32_e32 v242, 0x41b17218
	v_bfrev_b32_e32 v243, 0.5
	s_mov_b32 s55, 0x2e8ba2e9
	s_mov_b64 s[58:59], 0x100
	s_mov_b32 s64, 0x3e800000
	s_mov_b32 s48, s45
	v_writelane_b32 v254, s43, 63
	s_branch .LBB0_309

; #define PG8_STAGE(bufoff, gbase, voff) do { _Pragma("unroll") for (int _i = 0; _i < 2; ++_i) \
;         __builtin_amdgcn_global_load_lds((const unsigned*)((const char*)(gbase) + (voff)[_i]), (PG8_LAS unsigned*)(lds + (bufoff) + ldsw + _i * 8192), 16, 0, 0); } while (0)
; #define PG8_WAIT_V(n) asm volatile("s_waitcnt vmcnt(" #n ")" ::: "memory")
; #define PG8_BAR __builtin_amdgcn_s_barrier()
;     __device__ __forceinline__ size_t b_off(const pg8::Unit& u) const { return (size_t)(u.pm >> 3) * 4 * 131072; }
;     ...
;     unsigned voffA[2], voffB[2];
; #pragma unroll
;     for (int i = 0; i < 2; ++i) { int R, C; stage_rc(tid * 16 + i * 8192, R, C); const int Rb = Epi::PERM ? ((R & ~31) + perm32(R & 31)) : R;
;         const int Ra = ROWP ? (128 * (R >> 6) + 8 * (R & 15) + ((R >> 4) & 3)) : R;
;         voffA[i] = (unsigned)(Ra * LDA + C) * 2u; voffB[i] = (unsigned)(Rb * LDB + C) * 2u; }
;     ...
;     const char* cA = (const char*)g.A + (size_t)cur.pm * tstepA + (size_t)cur.pn * APN + kofA; const char* cB = (const char*)g.Bt + (size_t)cur.pn * tstepB + S.b_off(cur) + kofB;
;     S.a_ready(cur);
;     if constexpr (SP2) {
;         PG8_STAGE(PG8_SB(0, 0), cB, voffB); PG8_STAGE(PG8_SB(0, 1), cB + hstepB, voffB); PG8_STAGE(PG8_SA(0, 0), cA, voffA); PG8_STAGE(PG8_SA(0, 1), cA + hstepA, voffA);
;         P();
;         if (wr == 1) PG8_BAR;
;         PG8_WAIT_V(2); PG8_BAR;
;         PG8_STAGE(PG8_SB(1, 0), cB + kstep, voffB); PG8_STAGE(PG8_SA(1, 0), cA + kstepA, voffA); PG8_STAGE(PG8_SB(1, 1), cB + hstepB + kstep, voffB);
.LBB0_314:
	s_add_u32 s67, s76, s6
	s_addc_u32 s33, s77, s7
	s_add_u32 s10, s67, 0x34a04000
	s_addc_u32 s11, s33, 0
	s_add_u32 s12, s67, 0x3ca04000
	v_add_u32_e32 v181, s63, v180
	s_addc_u32 s13, s33, 0
	s_waitcnt vmcnt(0) lgkmcnt(0)
	v_mov_b32_e32 v2, v181
	s_cmpk_lt_i32 s85, 0x100
	s_cselect_b64 s[30:31], -1, 0
	s_cmpk_gt_i32 s85, 0xff
	v_readfirstlane_b32 s26, v2
	s_cbranch_scc1 .LBB0_631
	v_lshlrev_b32_e32 v0, 4, v2
	v_add_u32_e32 v4, 0x2000, v0
	v_ashrrev_i32_e32 v3, 31, v4
	v_lshrrev_b32_e32 v3, 22, v3
	v_add_u32_e32 v3, v4, v3
	v_ashrrev_i32_e32 v3, 10, v3
	v_mul_i32_i24_e32 v5, 0x400, v3
	v_sub_u32_e32 v4, v4, v5
	s_ashr_i32 s27, s26, 6
	v_lshrrev_b32_e32 v5, 4, v4
	s_lshl_b32 s2, s27, 10
	s_ashr_i32 s8, s85, 2
	s_and_b32 s41, s85, 3
	v_bitop3_b32 v5, v5, v4, 32 bitop3:0x6c
	s_add_u32 s61, s67, 0x20104000
	v_ashrrev_i32_e32 v4, 31, v5
	s_addc_u32 s63, s33, 0
	s_mul_i32 s7, s48, 0x1400000
	v_lshrrev_b32_e32 v4, 26, v4
	s_mul_hi_u32 s6, s48, 0x1400000
	s_add_u32 s7, s67, s7
	v_add_u32_e32 v6, v5, v4
	v_lshlrev_b32_e32 v7, 3, v3
	s_addc_u32 s6, s33, s6
	v_ashrrev_i32_e32 v4, 6, v6
	v_and_b32_e32 v7, -16, v7
	s_mov_b32 s14, s48
	s_add_u32 s48, s7, 0x704000
	v_add_u32_e32 v7, v4, v7
	s_addc_u32 s49, s6, 0
	v_and_b32_e32 v8, 3, v4
	s_mov_b32 s6, 0x1ffffe0
	v_lshrrev_b32_e32 v9, 2, v7
	v_lshlrev_b32_e32 v10, 1, v7
	v_and_b32_e32 v6, 0xc0, v6
	v_and_or_b32 v8, v7, s6, v8
	v_and_b32_e32 v9, 4, v9
	v_and_b32_e32 v10, 24, v10
	v_sub_u32_e32 v5, v5, v6
	v_or3_b32 v8, v8, v9, v10
	v_lshlrev_b32_e32 v9, 5, v3
	v_ashrrev_i16_sdwa v5, v241, sext(v5) dst_sel:DWORD dst_unused:UNUSED_PAD src0_sel:DWORD src1_sel:BYTE_0
	v_and_b32_e32 v9, 32, v9
	v_bfe_i32 v5, v5, 0, 16
	v_add_lshl_u32 v6, v9, v5, 1
	v_lshl_add_u32 v162, v8, 7, v6
	v_lshl_add_u32 v164, v7, 7, v6
	v_and_b32_e32 v220, 0x780, v164
	v_lshrrev_b32_e32 v220, 1, v220
	v_and_b32_e32 v221, 64, v164
	v_lshlrev_b32_e32 v221, 4, v221
	v_and_b32_e32 v222, 48, v164
	v_and_b32_e32 v164, 0x7800, v164
	v_or3_b32 v164, v164, v220, v221
	v_or_b32_e32 v164, v164, v222
	v_bfe_i32 v6, v2, 27, 1
	v_lshrrev_b32_e32 v6, 22, v6
	v_add_u32_e32 v6, v0, v6
	v_and_b32_e32 v6, 0xfffffc00, v6
	v_sub_u32_e32 v0, v0, v6
	v_lshrrev_b32_e32 v6, 4, v0
	v_ashrrev_i32_e32 v7, 31, v2
	v_bitop3_b32 v0, v6, v0, 32 bitop3:0x6c
	v_lshrrev_b32_e32 v7, 26, v7
	v_ashrrev_i32_e32 v6, 31, v0
	v_add_u32_e32 v7, v2, v7
	v_lshrrev_b32_e32 v6, 26, v6
	v_ashrrev_i32_e32 v7, 6, v7
	v_add_u32_e32 v8, v0, v6
	v_lshlrev_b32_e32 v9, 3, v7
	v_ashrrev_i32_e32 v6, 6, v8
	v_and_b32_e32 v9, -16, v9
	v_add_u32_e32 v9, v6, v9
	v_and_b32_e32 v10, 3, v6
	v_lshrrev_b32_e32 v11, 2, v9
	v_lshlrev_b32_e32 v12, 1, v9
	v_and_b32_e32 v8, 0xc0, v8
	v_and_or_b32 v10, v9, s6, v10
	v_and_b32_e32 v11, 4, v11
	v_and_b32_e32 v12, 24, v12
	v_sub_u32_e32 v0, v0, v8
	s_ashr_i32 s9, s8, 31
	v_or3_b32 v10, v10, v11, v12
	v_lshlrev_b32_e32 v11, 5, v7
	v_ashrrev_i16_sdwa v0, v241, sext(v0) dst_sel:DWORD dst_unused:UNUSED_PAD src0_sel:DWORD src1_sel:BYTE_0
	s_lshl_b64 s[6:7], s[8:9], 20
	s_lshl_b32 s9, s41, 20
	v_and_b32_e32 v11, 32, v11
	v_bfe_i32 v8, v0, 0, 16
	s_add_u32 s86, s48, s9
	v_add_lshl_u32 v11, v11, v8, 1
	s_addc_u32 s87, s49, 0
	s_add_i32 s51, s2, 0
	v_lshl_add_u32 v0, v10, 7, v11
	s_add_i32 m0, s51, 0x10000
	v_writelane_b32 v255, s14, 0
	global_load_lds_dwordx4 v0, s[86:87]
	s_add_i32 m0, s51, 0x12000
	v_writelane_b32 v255, s15, 1
	s_add_u32 s14, s86, 0x4000
	global_load_lds_dwordx4 v162, s[86:87]
	s_addc_u32 s15, s87, 0
	s_add_i32 m0, s51, 0x14000
	v_lshl_add_u32 v166, v9, 7, v11
	v_and_b32_e32 v220, 0x780, v166
	v_lshrrev_b32_e32 v220, 1, v220
	v_and_b32_e32 v221, 64, v166
	v_lshlrev_b32_e32 v221, 4, v221
	v_and_b32_e32 v222, 48, v166
	v_and_b32_e32 v166, 0x7800, v166
	v_or3_b32 v166, v166, v220, v221
	v_or_b32_e32 v166, v166, v222
	global_load_lds_dwordx4 v0, s[14:15]
	s_add_i32 m0, s51, 0x16000
	s_add_u32 s6, s61, s6
	s_addc_u32 s7, s63, s7
	s_add_i32 s92, s51, 0x2000
	global_load_lds_dwordx4 v162, s[14:15]
	s_mov_b32 m0, s51
	s_add_u32 s16, s6, 0x4000
	global_load_lds_dwordx4 v166, s[6:7]
	s_mov_b32 m0, s92
	s_addc_u32 s17, s7, 0
	s_add_i32 s14, s51, 0x4000
	global_load_lds_dwordx4 v164, s[6:7]
	s_mov_b32 m0, s14
	s_add_i32 s15, s51, 0x6000
	global_load_lds_dwordx4 v166, s[16:17]
	s_mov_b32 m0, s15
	v_ashrrev_i32_e32 v11, 8, v181
	global_load_lds_dwordx4 v164, s[16:17]
	s_mov_b32 s28, 0x66666667
	v_mul_hi_i32 v9, v11, s28
	v_lshrrev_b32_e32 v10, 31, v9
	v_ashrrev_i32_e32 v9, 1, v9
	v_add_u32_e32 v9, v9, v10
	v_mul_lo_u32 v9, v9, s38
	v_add_u32_e32 v13, s85, v9
	s_movk_i32 s9, 0x100
	v_cmp_gt_i32_e32 vcc, s9, v13
	s_and_saveexec_b64 s[16:17], vcc
	s_movk_i32 s9, 0xff
	s_cbranch_execz .LBB0_320
	v_and_b32_e32 v9, 0xff, v181
	v_lshlrev_b32_e32 v12, 2, v9
	s_add_u32 s18, s67, 0x304000
	v_add_u32_e32 v10, 2, v11
	v_lshl_or_b32 v11, v11, 10, v12
	v_readlane_b32 s20, v254, 52
	s_addc_u32 s19, s33, 0
	v_mov_b32_e32 v14, 0
	v_add_u32_e32 v11, s20, v11
	v_mov_b32_e32 v12, -1
	s_mov_b64 s[20:21], 0
	s_branch .LBB0_318

; #define PG8_STAGE(bufoff, gbase, voff) do { _Pragma("unroll") for (int _i = 0; _i < 2; ++_i) \
;         __builtin_amdgcn_global_load_lds((const unsigned*)((const char*)(gbase) + (voff)[_i]), (PG8_LAS unsigned*)(lds + (bufoff) + ldsw + _i * 8192), 16, 0, 0); } while (0)
; #define PG8_WAIT_V(n) asm volatile("s_waitcnt vmcnt(" #n ")" ::: "memory")
; #define PG8_BAR __builtin_amdgcn_s_barrier()
;     ...
;     const unsigned ldsw = (unsigned)wid * 1024u;
;     const int aoff = lds_byte(wr * 64 + fr, fq * 8), boff = lds_byte(wc * 32 + fr, fq * 8);
;     ...
;         PG8_STAGE(PG8_SB(1, 0), cB + kstep, voffB); PG8_STAGE(PG8_SA(1, 0), cA + kstepA, voffA); PG8_STAGE(PG8_SB(1, 1), cB + hstepB + kstep, voffB);
;         PG8_WAIT_V(6); PG8_BAR;
.LBB0_322:
	v_readlane_b32 s18, v255, 0
	v_readlane_b32 s19, v255, 1
	s_mov_b32 s20, s18
	s_mul_i32 s19, s20, 0x14000
	s_mul_hi_u32 s18, s18, 0x14000
	s_add_u32 s19, s67, s19
	s_addc_u32 s18, s33, s18
	s_add_u32 s70, s19, 0x204000
	s_addc_u32 s83, s18, 0
	s_lshl_b32 s44, s20, 10
	s_lshl_b64 s[18:19], s[44:45], 2
	s_add_u32 s18, s67, s18
	s_addc_u32 s19, s33, s19
	s_add_u32 s18, s18, 0x1c0000
	s_addc_u32 s19, s19, 0
	s_add_u32 s20, s67, 0x32a04000
	s_addc_u32 s21, s33, 0
	s_add_u32 s22, s67, 0x36a04000
	s_addc_u32 s23, s33, 0
	s_add_u32 s24, s67, 0x38a04000
	s_addc_u32 s25, s33, 0
	s_lshl_b32 s27, s27, 5
	s_and_b32 s81, s27, 0x60
	s_lshl_b32 s44, s9, 6
	s_lshl_b32 s30, s9, 13
	s_lshl_b32 s27, s81, 7
	s_add_u32 s28, s86, 0x8000
	s_addc_u32 s29, s87, 0
	s_add_i32 m0, s51, 0x18000
	s_waitcnt vmcnt(2)
	s_barrier
	global_load_lds_dwordx4 v0, s[28:29]
	s_add_i32 m0, s51, 0x1a000
	v_lshl_add_u64 v[10:11], s[28:29], 0, v[162:163]
	s_add_u32 s28, s6, 0x8000
	s_addc_u32 s29, s7, 0
	s_add_i32 s71, s51, 0x8000
	global_load_lds_dwordx4 v[10:11], off
	s_mov_b32 m0, s71
	s_add_i32 s80, s51, 0xa000
	global_load_lds_dwordx4 v166, s[28:29]
	v_lshl_add_u64 v[10:11], s[28:29], 0, v[164:165]
	s_add_u32 s28, s86, 0xc000
	s_mov_b32 m0, s80
	s_addc_u32 s29, s87, 0
	global_load_lds_dwordx4 v[10:11], off
	s_add_i32 m0, s51, 0x1c000
	s_nop 0
	global_load_lds_dwordx4 v0, s[28:29]
	v_lshl_add_u64 v[10:11], s[28:29], 0, v[162:163]
	s_add_i32 m0, s51, 0x1e000
	v_and_b32_e32 v9, 48, v2
	global_load_lds_dwordx4 v[10:11], off
	v_lshlrev_b32_e32 v10, 6, v2
	s_movk_i32 s28, 0x3c0
	v_lshlrev_b32_e32 v2, 2, v2
	v_and_or_b32 v9, v10, s28, v9
	v_and_b32_e32 v2, 32, v2
	v_bitop3_b32 v10, v9, s30, v2 bitop3:0xde
	v_bitop3_b32 v182, s27, v9, v2 bitop3:0xf6
	v_lshlrev_b32_e32 v2, 10, v7
	v_and_b32_e32 v2, 0xfffff800, v2
	v_lshl_add_u32 v2, v6, 7, v2
	v_and_b32_e32 v6, 1, v7
	v_lshl_or_b32 v2, v6, 6, v2
	v_lshl_add_u32 v168, v8, 1, v2
	v_and_b32_e32 v220, 0x780, v168
	v_lshrrev_b32_e32 v220, 1, v220
	v_and_b32_e32 v221, 64, v168
	v_lshlrev_b32_e32 v221, 4, v221
	v_and_b32_e32 v222, 48, v168
	v_and_b32_e32 v168, 0x7800, v168
	v_or3_b32 v168, v168, v220, v221
	v_or_b32_e32 v168, v168, v222
	v_lshlrev_b32_e32 v2, 10, v3
	s_cmpk_lt_u32 s26, 0x100
	v_and_b32_e32 v2, 0xfffff800, v2
	s_waitcnt vmcnt(6)
	s_cselect_b64 s[26:27], -1, 0
	s_lshl_b32 s9, s9, 8
	v_lshl_add_u32 v2, v4, 7, v2
	v_and_b32_e32 v3, 1, v3
	s_add_i32 s68, s9, 0
	v_lshl_or_b32 v2, v3, 6, v2
	s_add_i32 s68, s68, 0x20400
	v_mov_b32_e32 v169, v1
	v_lshl_add_u32 v170, v5, 1, v2
	v_and_b32_e32 v220, 0x780, v170
	v_lshrrev_b32_e32 v220, 1, v220
	v_and_b32_e32 v221, 64, v170
	v_lshlrev_b32_e32 v221, 4, v221
	v_and_b32_e32 v222, 48, v170
	v_and_b32_e32 v170, 0x7800, v170
	v_or3_b32 v170, v170, v220, v221
	v_or_b32_e32 v170, v170, v222
	v_mov_b32_e32 v171, v1
	s_mov_b32 s9, 0
	v_add_u32_e32 v183, 0, v10
	s_barrier
	s_branch .LBB0_325

; __device__ __forceinline__ float bperm(float v, int src_lane) { return __int_as_float(__builtin_amdgcn_ds_bpermute(src_lane << 2, __float_as_int(v))); }
; __device__ __forceinline__ u32x4 pack8(const f32x4 a, const f32x4 b) { u32x4 w; w.x = cvt_pk_bf16(a.x, a.y); w.y = cvt_pk_bf16(a.z, a.w); w.z = cvt_pk_bf16(b.x, b.y); w.w = cvt_pk_bf16(b.z, b.w); return w; }
; __host__ __device__ __forceinline__ size_t xs_off(int row, int col) { return (size_t)(row >> 8) * (256 * D) + (size_t)(col >> 6) * (256 * 64) + (size_t)((row & 255) * 64 + (col & 63)); }
;     template <bool INF32, int M0, int M1> __device__ __forceinline__ void half(f32x4 (&acc)[2][2][4][2], int ai, int b, int row0, int col, int pn, int wc, int fr, int fq) const {
;     ...
;         for (int m = M0; m < M1; ++m) { const int row = row0 + ai * 128 + m * 16; float ss = 0.f;
; #pragma unroll
;             for (int bj = 0; bj < 2; ++bj) { const size_t o = (size_t)row * D + col + bj * 128;
;                 const f32x4 x0 = xv[m][bj][0] + gt[bj][0] * acc[ai][bj][m][0], x1 = xv[m][bj][1] + gt[bj][1] * acc[ai][bj][m][1];
;                 if (out_f32) { *(f32x4*)((float*)xout + o) = x0; *(f32x4*)((float*)xout + o + 4) = x1; }
;                 else { const f32x8_t ff = {x0.x, x0.y, x0.z, x0.w, x1.x, x1.y, x1.z, x1.w}; *(f16x8_t*)((bf16_t*)xout + o) = __builtin_convertvector(ff, f16x8_t); }
;                 ss += ((x0.x * x0.x + x0.y * x0.y) + (x0.z * x0.z + x0.w * x0.w)) + ((x1.x * x1.x + x1.y * x1.y) + (x1.z * x1.z + x1.w * x1.w));
;                 if (XS) *(u32x4*)(XS + xs_off(row0, col) + (ai * 128 + m * 16) * 64 + bj * (2 * 256 * 64)) = pack8(x0 * gs[bj][0], x1 * gs[bj][1]); }
;             { const int ln = fr + 16 * fq; ss += bperm(ss, ln ^ 16); ss += bperm(ss, ln ^ 32); }
;             if (fq == 0) RSS[(size_t)row * 32 + pn * 4 + wc] = ss; }
;     }
;     __device__ __forceinline__ void operator()(f32x4 (&acc)[2][2][4][2], const pg8::Unit& u, int ui, int wr, int wc, int fr, int fq) const {
;         const int b = u.pm >> 4, row0 = u.pm * 256 + wr * 64 + fr, col = u.pn * 256 + wc * 32 + fq * 8;
.LBB0_1131:
	s_mul_i32 s100, s30, 0x1e00
	s_mul_i32 s101, s81, 62
	s_add_u32 s100, s100, s101
	s_mov_b32 s101, 0
	v_mbcnt_lo_u32_b32 v247, -1, 0
	v_mbcnt_hi_u32_b32 v247, -1, v247
	s_lshl_b32 s31, s28, 8
	v_ashrrev_i32_e32 v130, 4, v247
	v_and_b32_e32 v0, 15, v247
	s_add_i32 s31, s31, s80
	v_lshl_add_u32 v131, v130, 3, s81
	v_or_b32_e32 v200, s31, v0
	v_lshl_add_u32 v198, s30, 8, v131
	s_ashr_i32 s36, s28, 4
	v_ashrrev_i32_e32 v199, 31, v198
	v_or_b32_e32 v206, 16, v200
	v_or_b32_e32 v204, 32, v200
	v_or_b32_e32 v202, 48, v200
	v_lshlrev_b32_e32 v132, 6, v200
	v_and_b32_e32 v131, 56, v131
	v_lshlrev_b32_e32 v130, 6, v130
	v_lshlrev_b32_e32 v0, 2, v0
	s_movk_i32 s12, 0x33c0
	s_and_b64 vcc, exec, s[94:95]
	v_ashrrev_i32_e32 v201, 31, v200
	s_mul_hi_i32 s65, s36, 0xc000
	s_mul_i32 s66, s36, 0xc000
	v_lshlrev_b64 v[146:147], 2, v[198:199]
	v_cmp_gt_u32_e64 s[28:29], 16, v247
	v_ashrrev_i32_e32 v207, 31, v206
	v_ashrrev_i32_e32 v205, 31, v204
	v_ashrrev_i32_e32 v203, 31, v202
	v_ashrrev_i32_e32 v208, 6, v198
	v_and_or_b32 v246, v132, s12, v131
	v_and_b32_e32 v248, 0x3c0, v246
	v_lshrrev_b32_e32 v248, 1, v248
	v_and_b32_e32 v249, 32, v246
	v_lshlrev_b32_e32 v249, 4, v249
	v_and_b32_e32 v246, 0x1018, v246
	v_or3_b32 v246, v246, v248, v249
	v_bitop3_b32 v245, v130, 64, v0 bitop3:0x36
	v_bitop3_b32 v244, v130, s84, v0 bitop3:0x36
	s_cbranch_vccz .LBB0_1149
; __device__ __forceinline__ float bperm(float v, int src_lane) { return __int_as_float(__builtin_amdgcn_ds_bpermute(src_lane << 2, __float_as_int(v))); }
;     template <bool INF32, int M0, int M1> __device__ __forceinline__ void half(f32x4 (&acc)[2][2][4][2], int ai, int b, int row0, int col, int pn, int wc, int fr, int fq) const {
;     ...
;             for (int m = M0; m < M1; ++m)
; #pragma unroll
;                 for (int bj = 0; bj < 2; ++bj) hh[m][bj] = *(const f16x8_t*)((const bf16_t*)xin + (size_t)(row0 + ai * 128 + m * 16) * D + col + bj * 128);
; #pragma unroll
;             for (int m = M0; m < M1; ++m)
; #pragma unroll
;                 for (int bj = 0; bj < 2; ++bj) { const f32x8_t ff = __builtin_convertvector(hh[m][bj], f32x8_t); xv[m][bj][0] = (f32x4){ff[0], ff[1], ff[2], ff[3]}; xv[m][bj][1] = (f32x4){ff[4], ff[5], ff[6], ff[7]}; }
;         }
;         f32x4 gt[2][2], gs[2][2];
; #pragma unroll
;         for (int bj = 0; bj < 2; ++bj)
; #pragma unroll
;             for (int n = 0; n < 2; ++n) { gt[bj][n] = *(const f32x4*)(gate + (size_t)b * 6 * D + col + bj * 128 + n * 4); gs[bj][n] = XS ? *(const f32x4*)(GS + (size_t)b * D + col + bj * 128 + n * 4) : (f32x4){0.f, 0.f, 0.f, 0.f}; }
;         __builtin_amdgcn_sched_barrier(0);
; #pragma unroll
;         for (int m = M0; m < M1; ++m) { const int row = row0 + ai * 128 + m * 16; float ss = 0.f;
; #pragma unroll
;             for (int bj = 0; bj < 2; ++bj) { const size_t o = (size_t)row * D + col + bj * 128;
;                 const f32x4 x0 = xv[m][bj][0] + gt[bj][0] * acc[ai][bj][m][0], x1 = xv[m][bj][1] + gt[bj][1] * acc[ai][bj][m][1];
;                 if (out_f32) { *(f32x4*)((float*)xout + o) = x0; *(f32x4*)((float*)xout + o + 4) = x1; }
;                 else { const f32x8_t ff = {x0.x, x0.y, x0.z, x0.w, x1.x, x1.y, x1.z, x1.w}; *(f16x8_t*)((bf16_t*)xout + o) = __builtin_convertvector(ff, f16x8_t); }
;                 ss += ((x0.x * x0.x + x0.y * x0.y) + (x0.z * x0.z + x0.w * x0.w)) + ((x1.x * x1.x + x1.y * x1.y) + (x1.z * x1.z + x1.w * x1.w));
;                 if (XS) *(u32x4*)(XS + xs_off(row0, col) + (ai * 128 + m * 16) * 64 + bj * (2 * 256 * 64)) = pack8(x0 * gs[bj][0], x1 * gs[bj][1]); }
;             { const int ln = fr + 16 * fq; ss += bperm(ss, ln ^ 16); ss += bperm(ss, ln ^ 32); }
;             if (fq == 0) RSS[(size_t)row * 32 + pn * 4 + wc] = ss; }
	v_lshlrev_b64 v[212:213], 1, v[198:199]
	v_lshl_add_u64 v[212:213], v[212:213], 0, s[100:101]
	v_lshl_add_u64 v[220:221], s[10:11], 0, v[212:213]
	v_lshlrev_b64 v[214:215], 12, v[200:201]
	v_bfe_u32 v215, v214, 12, 4
	v_lshl_add_u32 v214, v215, 6, v214
	v_lshlrev_b32_e32 v215, 12, v215
	v_sub_u32_e32 v214, v214, v215
	v_mov_b32_e32 v215, 0
	v_lshl_add_u64 v[134:135], v[220:221], 0, v[214:215]
	global_load_dwordx4 v[130:133], v[134:135], off
	s_nop 0
	global_load_dwordx4 v[134:137], v[134:135], off offset:1024
	s_ashr_i32 s37, s36, 31
	s_add_u32 s34, s63, s66
	v_lshlrev_b64 v[228:229], 12, v[206:207]
	v_bfe_u32 v229, v228, 12, 4
	v_lshl_add_u32 v228, v229, 6, v228
	v_lshlrev_b32_e32 v229, 12, v229
	v_sub_u32_e32 v228, v228, v229
	v_mov_b32_e32 v229, 0
	s_addc_u32 s35, s67, s65
	v_lshl_add_u64 v[138:139], v[220:221], 0, v[228:229]
	v_lshlrev_b64 v[226:227], 12, v[204:205]
	v_bfe_u32 v227, v226, 12, 4
	v_lshl_add_u32 v226, v227, 6, v226
	v_lshlrev_b32_e32 v227, 12, v227
	v_sub_u32_e32 v226, v226, v227
	v_mov_b32_e32 v227, 0
	v_lshl_add_u64 v[222:223], s[34:35], 0, v[146:147]
	s_lshl_b64 s[34:35], s[36:37], 13
	global_load_dwordx4 v[182:185], v[138:139], off
	global_load_dwordx4 v[178:181], v[138:139], off offset:1024
	v_lshl_add_u64 v[138:139], v[220:221], 0, v[226:227]
	v_lshlrev_b64 v[218:219], 12, v[202:203]
	v_bfe_u32 v219, v218, 12, 4
	v_lshl_add_u32 v218, v219, 6, v218
	v_lshlrev_b32_e32 v219, 12, v219
	v_sub_u32_e32 v218, v218, v219
	v_mov_b32_e32 v219, 0
	s_add_u32 s34, s68, s34
	global_load_dwordx4 v[174:177], v[138:139], off
	global_load_dwordx4 v[170:173], v[138:139], off offset:1024
	v_lshl_add_u64 v[138:139], v[220:221], 0, v[218:219]
	s_addc_u32 s35, s70, s35
	global_load_dwordx4 v[142:145], v[138:139], off
	s_nop 0
	global_load_dwordx4 v[138:141], v[138:139], off offset:1024
	v_lshl_add_u64 v[224:225], s[34:35], 0, v[146:147]
	s_waitcnt vmcnt(0)
	v_cvt_f32_f16_e32 v216, v132
	v_cvt_f32_f16_sdwa v217, v132 dst_sel:DWORD dst_unused:UNUSED_PAD src0_sel:WORD_1
	v_cvt_f32_f16_e32 v234, v133
	v_cvt_f32_f16_sdwa v235, v133 dst_sel:DWORD dst_unused:UNUSED_PAD src0_sel:WORD_1
	v_cvt_f32_f16_e32 v236, v130
	v_cvt_f32_f16_sdwa v237, v130 dst_sel:DWORD dst_unused:UNUSED_PAD src0_sel:WORD_1
	v_cvt_f32_f16_e32 v248, v131
	v_cvt_f32_f16_sdwa v249, v131 dst_sel:DWORD dst_unused:UNUSED_PAD src0_sel:WORD_1
	v_cvt_f32_f16_e32 v230, v136
	v_cvt_f32_f16_sdwa v231, v136 dst_sel:DWORD dst_unused:UNUSED_PAD src0_sel:WORD_1
	v_cvt_f32_f16_e32 v232, v137
	v_cvt_f32_f16_sdwa v233, v137 dst_sel:DWORD dst_unused:UNUSED_PAD src0_sel:WORD_1
	v_cvt_f32_f16_e32 v250, v134
	v_cvt_f32_f16_sdwa v251, v134 dst_sel:DWORD dst_unused:UNUSED_PAD src0_sel:WORD_1
	v_cvt_f32_f16_e32 v252, v135
	v_cvt_f32_f16_sdwa v253, v135 dst_sel:DWORD dst_unused:UNUSED_PAD src0_sel:WORD_1
	global_load_dwordx4 v[162:165], v[222:223], off offset:16
	global_load_dwordx4 v[166:169], v[222:223], off
	global_load_dwordx4 v[154:157], v[224:225], off offset:16
	global_load_dwordx4 v[158:161], v[224:225], off
	global_load_dwordx4 v[146:149], v[222:223], off offset:528
	global_load_dwordx4 v[150:153], v[222:223], off offset:512
	global_load_dwordx4 v[130:133], v[224:225], off offset:528
	global_load_dwordx4 v[134:137], v[224:225], off offset:512
	v_ashrrev_i32_e32 v209, 31, v208
	s_waitcnt vmcnt(6)
	v_pk_fma_f32 v[248:249], v[128:129], v[168:169], v[248:249]
	v_pk_fma_f32 v[240:241], v[126:127], v[166:167], v[236:237]
	v_lshlrev_b64 v[238:239], 15, v[208:209]
	v_mul_f32_e32 v0, v241, v241
	v_mul_f32_e32 v209, v249, v249
	v_pk_fma_f32 v[210:211], v[124:125], v[164:165], v[234:235]
	v_pk_fma_f32 v[216:217], v[122:123], v[162:163], v[216:217]
	v_lshl_add_u64 v[214:215], s[10:11], 0, v[214:215]
	v_fmac_f32_e32 v0, v240, v240
	v_fmac_f32_e32 v209, v248, v248
	s_ashr_i32 s34, s31, 8
	v_cvt_pk_f16_f32 v237, v210, v211
	v_cvt_pk_f16_f32 v235, v248, v249
	v_cvt_pk_f16_f32 v236, v216, v217
	v_cvt_pk_f16_f32 v234, v240, v241
	v_lshl_add_u64 v[212:213], v[214:215], 0, v[212:213]
	v_add_f32_e32 v0, v0, v209
	v_mul_f32_e32 v209, v217, v217
	v_mul_f32_e32 v214, v211, v211
	s_ashr_i32 s35, s34, 31
	global_store_dwordx4 v[212:213], v[234:237], off
	v_fmac_f32_e32 v209, v216, v216
	v_fmac_f32_e32 v214, v210, v210
	s_waitcnt vmcnt(5)
	v_pk_mul_f32 v[234:235], v[158:159], v[240:241]
	v_pk_mul_f32 v[210:211], v[156:157], v[210:211]
	s_lshl_b64 s[46:47], s[34:35], 20
	v_add_f32_e32 v209, v209, v214
	v_pk_mul_f32 v[214:215], v[160:161], v[248:249]
	v_pk_mul_f32 v[216:217], v[154:155], v[216:217]
	v_cvt_pk_bf16_f32 v234, v234, v235
	v_cvt_pk_bf16_f32 v235, v214, v215
	v_add_f32_e32 v209, v0, v209
	v_cvt_pk_bf16_f32 v236, v216, v217
	v_cvt_pk_bf16_f32 v237, v210, v211
	v_lshl_add_u64 v[210:211], s[74:75], 0, v[238:239]
	v_lshl_add_u64 v[210:211], v[210:211], 0, s[46:47]
	v_lshlrev_b32_e32 v0, 1, v246
	v_lshl_add_u64 v[216:217], v[210:211], 0, v[0:1]
	global_store_dwordx4 v[216:217], v[234:237], off
	s_waitcnt vmcnt(4)
	v_pk_fma_f32 v[210:211], v[120:121], v[152:153], v[252:253]
	v_pk_fma_f32 v[214:215], v[118:119], v[150:151], v[250:251]
	v_pk_fma_f32 v[234:235], v[116:117], v[148:149], v[232:233]
	v_pk_fma_f32 v[236:237], v[114:115], v[146:147], v[230:231]
	v_cvt_pk_f16_f32 v233, v234, v235
	v_cvt_pk_f16_f32 v231, v210, v211
	v_cvt_pk_f16_f32 v232, v236, v237
	v_cvt_pk_f16_f32 v230, v214, v215
	global_store_dwordx4 v[212:213], v[230:233], off offset:1024
	v_mul_f32_e32 v0, v215, v215
	v_mul_f32_e32 v212, v211, v211
	v_fmac_f32_e32 v0, v214, v214
	v_fmac_f32_e32 v212, v210, v210
	v_add_f32_e32 v0, v0, v212
	v_mul_f32_e32 v212, v237, v237
	v_mul_f32_e32 v213, v235, v235
	v_fmac_f32_e32 v212, v236, v236
	v_fmac_f32_e32 v213, v234, v234
	v_add_f32_e32 v212, v212, v213
	v_add_f32_e32 v0, v0, v212
	v_add_f32_e32 v0, v209, v0
	ds_bpermute_b32 v209, v245, v0
	s_waitcnt vmcnt(3)
	v_pk_mul_f32 v[210:211], v[136:137], v[210:211]
	s_lshl_b32 s34, s30, 2
	v_pk_mul_f32 v[212:213], v[134:135], v[214:215]
	s_ashr_i32 s35, s34, 31
	s_waitcnt lgkmcnt(0)
	v_add_f32_e32 v0, v0, v209
	ds_bpermute_b32 v209, v244, v0
	v_cvt_pk_bf16_f32 v230, v212, v213
	v_cvt_pk_bf16_f32 v231, v210, v211
	v_add_co_u32_e32 v210, vcc, 0x10000, v216
	v_pk_mul_f32 v[232:233], v[130:131], v[236:237]
	s_nop 0
	v_addc_co_u32_e32 v211, vcc, 0, v217, vcc
	v_pk_mul_f32 v[214:215], v[132:133], v[234:235]
	v_cvt_pk_bf16_f32 v232, v232, v233
	s_nop 0
	v_cvt_pk_bf16_f32 v233, v214, v215
	global_store_dwordx4 v[210:211], v[230:233], off
	s_and_saveexec_b64 s[46:47], s[28:29]
	s_cbranch_execz .LBB0_1134
	v_lshlrev_b64 v[210:211], 7, v[200:201]
	v_lshl_add_u64 v[210:211], s[42:43], 0, v[210:211]
	v_lshl_add_u64 v[210:211], s[34:35], 2, v[210:211]
	s_lshl_b32 s44, s71, 2
	v_lshl_add_u64 v[210:211], v[210:211], 0, s[44:45]
	s_waitcnt lgkmcnt(0)
	v_add_f32_e32 v0, v0, v209
	global_store_dword v[210:211], v0, off

; #define PG8_STAGE(bufoff, gbase, voff) do { _Pragma("unroll") for (int _i = 0; _i < 2; ++_i) \
;         __builtin_amdgcn_global_load_lds((const unsigned*)((const char*)(gbase) + (voff)[_i]), (PG8_LAS unsigned*)(lds + (bufoff) + ldsw + _i * 8192), 16, 0, 0); } while (0)
;     __device__ __forceinline__ size_t b_off(const pg8::Unit& u) const { return (size_t)(u.pm >> 3) * 4 * 131072; }
;     ...
;     for (int i = 0; i < 2; ++i) { int R, C; stage_rc(tid * 16 + i * 8192, R, C); const int Rb = Epi::PERM ? ((R & ~31) + perm32(R & 31)) : R;
;         const int Ra = ROWP ? (128 * (R >> 6) + 8 * (R & 15) + ((R >> 4) & 3)) : R;
;         voffA[i] = (unsigned)(Ra * LDA + C) * 2u; voffB[i] = (unsigned)(Rb * LDB + C) * 2u; }
;     ...
;     const char* cA = (const char*)g.A + (size_t)cur.pm * tstepA + (size_t)cur.pn * APN + kofA; const char* cB = (const char*)g.Bt + (size_t)cur.pn * tstepB + S.b_off(cur) + kofB;
;     S.a_ready(cur);
;     if constexpr (SP2) {
;         PG8_STAGE(PG8_SB(0, 0), cB, voffB); PG8_STAGE(PG8_SB(0, 1), cB + hstepB, voffB); PG8_STAGE(PG8_SA(0, 0), cA, voffA); PG8_STAGE(PG8_SA(0, 1), cA + hstepA, voffA);
.LBB0_1240:
	s_andn2_b64 vcc, exec, s[6:7]
	s_cbranch_vccnz .LBB0_1340
	s_mov_b32 s8, s70
	s_mov_b64 s[6:7], 0
	v_mbcnt_lo_u32_b32 v0, -1, 0
	v_mbcnt_hi_u32_b32 v0, -1, v0
	s_cmpk_gt_i32 s8, 0xaff
	s_waitcnt vmcnt(0) lgkmcnt(0)
	v_add_u32_e32 v2, s63, v0
	v_mov_b32_e32 v0, v2
	s_nop 0
	v_readfirstlane_b32 s19, v0
	s_cbranch_scc1 .LBB0_1269
	v_lshlrev_b32_e32 v3, 4, v0
	v_add_u32_e32 v5, 0x2000, v3
	v_ashrrev_i32_e32 v4, 31, v5
	v_lshrrev_b32_e32 v4, 22, v4
	v_add_u32_e32 v4, v5, v4
	v_ashrrev_i32_e32 v4, 10, v4
	v_mul_i32_i24_e32 v6, 0x400, v4
	v_sub_u32_e32 v5, v5, v6
	v_lshrrev_b32_e32 v6, 4, v5
	v_bitop3_b32 v5, v6, v5, 32 bitop3:0x6c
	v_ashrrev_i32_e32 v6, 31, v5
	v_lshrrev_b32_e32 v6, 26, v6
	v_add_u32_e32 v6, v5, v6
	v_lshlrev_b32_e32 v8, 3, v4
	v_ashrrev_i32_e32 v7, 6, v6
	v_and_b32_e32 v8, -16, v8
	v_add_u32_e32 v8, v7, v8
	v_and_b32_e32 v7, 3, v7
	s_mov_b32 s9, 0x1ffffe0
	v_lshrrev_b32_e32 v9, 2, v8
	v_lshlrev_b32_e32 v10, 1, v8
	v_and_b32_e32 v6, 0xc0, v6
	v_and_or_b32 v7, v8, s9, v7
	v_and_b32_e32 v9, 4, v9
	v_and_b32_e32 v11, 24, v10
	v_sub_u32_e32 v5, v5, v6
	v_or3_b32 v7, v7, v9, v11
	v_lshlrev_b32_e32 v9, 5, v4
	v_ashrrev_i16_sdwa v5, v241, sext(v5) dst_sel:DWORD dst_unused:UNUSED_PAD src0_sel:DWORD src1_sel:BYTE_0
	v_and_b32_e32 v9, 32, v9
	v_bfe_i32 v5, v5, 0, 16
	v_add_lshl_u32 v9, v9, v5, 1
	v_lshl_add_u32 v158, v7, 7, v9
	v_lshlrev_b32_e32 v7, 3, v8
	v_and_b32_e32 v6, 0x1ffff80, v10
	v_and_b32_e32 v7, 0x78, v7
	v_bfe_u32 v8, v8, 4, 2
	v_or3_b32 v10, v6, v7, v8
	v_lshl_add_u32 v160, v10, 7, v9
	v_and_b32_e32 v220, 0x780, v160
	v_lshrrev_b32_e32 v220, 1, v220
	v_and_b32_e32 v221, 64, v160
	v_lshlrev_b32_e32 v221, 4, v221
	v_and_b32_e32 v222, 48, v160
	v_and_b32_e32 v160, 0x7800, v160
	v_or3_b32 v160, v160, v220, v221
	v_or_b32_e32 v160, v160, v222
	v_bfe_i32 v9, v0, 27, 1
	v_lshrrev_b32_e32 v9, 22, v9
	v_add_u32_e32 v9, v3, v9
	v_and_b32_e32 v9, 0xfffffc00, v9
	v_sub_u32_e32 v3, v3, v9
	v_lshrrev_b32_e32 v9, 4, v3
	v_bitop3_b32 v3, v9, v3, 32 bitop3:0x6c
	s_add_u32 s22, s76, s6
	v_ashrrev_i32_e32 v9, 31, v3
	s_addc_u32 s23, s77, s7
	v_lshrrev_b32_e32 v9, 26, v9
	s_add_u32 s2, s22, 0x20104000
	v_add_u32_e32 v10, v3, v9
	v_ashrrev_i32_e32 v9, 31, v0
	s_addc_u32 s33, s23, 0
	s_mul_i32 s7, s48, 0x2c00000
	v_lshrrev_b32_e32 v9, 26, v9
	s_mul_hi_u32 s6, s48, 0x2c00000
	s_add_u32 s7, s22, s7
	v_add_u32_e32 v9, v0, v9
	s_addc_u32 s6, s23, s6
	v_ashrrev_i32_e32 v9, 6, v9
	s_add_u32 s40, s7, 0x7704000
	v_lshlrev_b32_e32 v12, 3, v9
	s_addc_u32 s41, s6, 0
	v_ashrrev_i32_e32 v11, 6, v10
	v_and_b32_e32 v12, -16, v12
	s_mov_b32 s10, s48
	s_add_u32 s6, s22, 0x504000
	v_add_u32_e32 v13, v11, v12
	v_and_b32_e32 v11, 3, v11
	v_writelane_b32 v255, s10, 0
	s_addc_u32 s7, s23, 0
	v_and_or_b32 v11, v13, s9, v11
	s_ashr_i32 s9, s8, 31
	v_writelane_b32 v255, s11, 1
	s_lshr_b32 s10, s9, 29
	s_add_i32 s10, s8, s10
	s_ashr_i32 s24, s19, 6
	s_ashr_i32 s11, s10, 3
	s_and_b32 s10, s10, -8
	s_lshl_b32 s44, s24, 10
	s_sub_i32 s10, s8, s10
	s_cmp_lt_i32 s10, 0
	s_movk_i32 s12, 0x161
	s_cselect_b32 s12, s12, 0x160
	s_mul_i32 s10, s10, s12
	s_add_i32 s10, s10, s11
	s_mul_hi_i32 s11, s10, 0x2e8ba2e9
	s_lshr_b32 s12, s11, 31
	s_ashr_i32 s11, s11, 6
	s_add_i32 s11, s11, s12
	s_lshl_b32 s12, s11, 3
	s_mulk_i32 s11, 0x160
	s_sub_i32 s10, s10, s11
	s_bfe_u32 s11, s10, 0x3001c
	s_add_i32 s11, s10, s11
	s_sext_i32_i16 s13, s11
	s_and_b32 s11, s11, 0xfff8
	s_sub_i32 s10, s10, s11
	s_sext_i32_i16 s10, s10
	v_lshrrev_b32_e32 v12, 2, v13
	v_lshlrev_b32_e32 v14, 1, v13
	v_and_b32_e32 v10, 0xc0, v10
	s_lshr_b32 s18, s13, 3
	s_add_i32 s10, s12, s10
	v_and_b32_e32 v12, 4, v12
	v_and_b32_e32 v15, 24, v14
	v_sub_u32_e32 v3, v3, v10
	s_ashr_i32 s11, s10, 31
	s_bfe_i64 s[14:15], s[18:19], 0x100000
	v_or3_b32 v11, v11, v12, v15
	v_lshlrev_b32_e32 v12, 5, v9
	v_ashrrev_i16_sdwa v3, v241, sext(v3) dst_sel:DWORD dst_unused:UNUSED_PAD src0_sel:DWORD src1_sel:BYTE_0
	s_lshl_b64 s[12:13], s[10:11], 20
	s_lshl_b64 s[14:15], s[14:15], 20
	v_and_b32_e32 v12, 32, v12
	v_bfe_i32 v10, v3, 0, 16
	s_add_u32 s36, s40, s14
	v_add_lshl_u32 v3, v12, v10, 1
	s_addc_u32 s37, s41, s15
	s_add_i32 s48, s44, 0
	v_lshl_add_u32 v162, v11, 7, v3
	s_add_i32 m0, s48, 0x10000
	v_lshlrev_b32_e32 v12, 3, v13
	global_load_lds_dwordx4 v162, s[36:37]
	s_add_i32 m0, s48, 0x12000
	s_add_u32 s14, s36, 0x4000
	global_load_lds_dwordx4 v158, s[36:37]
	s_addc_u32 s15, s37, 0
	s_add_i32 m0, s48, 0x14000
	v_and_b32_e32 v11, 0x1ffff80, v14
	v_and_b32_e32 v12, 0x78, v12
	v_bfe_u32 v13, v13, 4, 2
	global_load_lds_dwordx4 v162, s[14:15]
	s_add_i32 m0, s48, 0x16000
	v_or3_b32 v14, v11, v12, v13
	s_add_u32 s34, s2, s12
	v_lshl_add_u32 v164, v14, 7, v3
	v_and_b32_e32 v220, 0x780, v164
	v_lshrrev_b32_e32 v220, 1, v220
	v_and_b32_e32 v221, 64, v164
	v_lshlrev_b32_e32 v221, 4, v221
	v_and_b32_e32 v222, 48, v164
	v_and_b32_e32 v164, 0x7800, v164
	v_or3_b32 v164, v164, v220, v221
	v_or_b32_e32 v164, v164, v222
	global_load_lds_dwordx4 v158, s[14:15]
	s_addc_u32 s35, s33, s13
	v_mov_b32_e32 v165, v1
	s_mov_b32 m0, s48
	s_add_i32 s49, s48, 0x2000
	v_lshl_add_u64 v[14:15], s[34:35], 0, v[164:165]
	global_load_lds_dwordx4 v164, s[34:35]
	v_mov_b32_e32 v161, v1
	s_mov_b32 m0, s49
	s_add_i32 s51, s48, 0x4000
	v_lshl_add_u64 v[16:17], s[34:35], 0, v[160:161]
	global_load_lds_dwordx4 v160, s[34:35]
	v_lshl_add_u64 v[14:15], v[14:15], 0, s[58:59]
	s_mov_b32 m0, s51
	s_add_i32 s54, s48, 0x6000
	global_load_lds_dwordx4 v[14:15], off
	v_lshl_add_u64 v[14:15], v[16:17], 0, s[58:59]
	s_mov_b32 m0, s54
	v_ashrrev_i32_e32 v16, 8, v2
	global_load_lds_dwordx4 v[14:15], off
	v_and_b32_e32 v14, 0xff, v2
	v_lshlrev_b32_e32 v2, 2, v14
	v_lshl_or_b32 v2, v16, 10, v2
	v_readlane_b32 s11, v254, 52
	v_readlane_b32 s28, v254, 48
	v_mov_b32_e32 v163, v1
	v_add_u32_e32 v15, s11, v2
	v_mov_b64_e32 v[2:3], s[8:9]
	v_mad_i64_i32 v[2:3], s[12:13], s38, v16, v[2:3]
	v_mov_b32_e32 v159, v1
	v_mov_b32_e32 v18, -1
	v_mov_b32_e32 v17, 0
	s_mov_b64 s[12:13], 0
	v_readlane_b32 s29, v254, 49
	s_branch .LBB0_1245

; #define PG8_STAGE(bufoff, gbase, voff) do { _Pragma("unroll") for (int _i = 0; _i < 2; ++_i) \
;         __builtin_amdgcn_global_load_lds((const unsigned*)((const char*)(gbase) + (voff)[_i]), (PG8_LAS unsigned*)(lds + (bufoff) + ldsw + _i * 8192), 16, 0, 0); } while (0)
; #define PG8_WAIT_V(n) asm volatile("s_waitcnt vmcnt(" #n ")" ::: "memory")
; #define PG8_BAR __builtin_amdgcn_s_barrier()
;     ...
;     const unsigned ldsw = (unsigned)wid * 1024u;
;     const int aoff = lds_byte(wr * 64 + fr, fq * 8), boff = lds_byte(wc * 32 + fr, fq * 8);
;     ...
;         PG8_STAGE(PG8_SB(1, 0), cB + kstep, voffB); PG8_STAGE(PG8_SA(1, 0), cA + kstepA, voffA); PG8_STAGE(PG8_SB(1, 1), cB + hstepB + kstep, voffB);
;         PG8_WAIT_V(6); PG8_BAR;
.LBB0_1250:
	v_readlane_b32 s6, v255, 0
	v_readlane_b32 s7, v255, 1
	s_mov_b32 s20, s6
	s_mul_i32 s7, s20, 0x2c000
	s_mul_hi_u32 s6, s6, 0x2c000
	s_add_u32 s7, s22, s7
	s_addc_u32 s6, s23, s6
	v_readlane_b32 s80, v254, 14
	s_add_u32 s61, s7, 0x254000
	v_readlane_b32 s90, v254, 24
	v_readlane_b32 s91, v254, 25
	s_addc_u32 s63, s6, 0
	s_mul_i32 s7, s20, 0x10800
	s_mov_b64 s[14:15], s[90:91]
	s_mul_hi_u32 s6, s20, 0x10800
	v_readlane_b32 s92, v254, 26
	v_readlane_b32 s93, v254, 27
	s_add_u32 s14, s14, s7
	s_mov_b64 s[16:17], s[92:93]
	s_addc_u32 s15, s15, s6
	s_mul_i32 s7, s20, 0x5800
	s_mul_hi_u32 s6, s20, 0x5800
	s_add_u32 s16, s16, s7
	s_addc_u32 s17, s17, s6
	s_add_u32 s67, s22, 0x24104000
	s_addc_u32 s68, s23, 0
	s_add_u32 s70, s22, 0x2f104000
	s_addc_u32 s71, s23, 0
	v_readlane_b32 s81, v254, 15
	s_add_u32 s80, s22, 0x30704000
	v_readlane_b32 s83, v254, 17
	s_addc_u32 s81, s23, 0
	s_lshl_b32 s6, s24, 5
	s_and_b32 s83, s6, 0x60
	s_lshl_b32 s20, s55, 13
	s_lshl_b32 s21, s83, 7
	s_add_u32 s6, s36, 0x8000
	s_addc_u32 s7, s37, 0
	s_add_i32 m0, s48, 0x18000
	s_waitcnt vmcnt(2)
	s_barrier
	global_load_lds_dwordx4 v162, s[6:7]
	s_add_i32 m0, s48, 0x1a000
	v_readlane_b32 s85, v254, 19
	v_lshl_add_u64 v[2:3], s[6:7], 0, v[158:159]
	s_add_u32 s6, s34, 0x8000
	s_addc_u32 s7, s35, 0
	s_add_i32 s85, s48, 0x8000
	global_load_lds_dwordx4 v[2:3], off
	s_mov_b32 m0, s85
	s_add_i32 s90, s48, 0xa000
	global_load_lds_dwordx4 v164, s[6:7]
	v_lshl_add_u64 v[2:3], s[6:7], 0, v[160:161]
	s_add_u32 s6, s36, 0xc000
	s_mov_b32 m0, s90
	s_addc_u32 s7, s37, 0
	global_load_lds_dwordx4 v[2:3], off
	s_add_i32 m0, s48, 0x1c000
	s_nop 0
	global_load_lds_dwordx4 v162, s[6:7]
	v_lshl_add_u64 v[2:3], s[6:7], 0, v[158:159]
	s_add_i32 m0, s48, 0x1e000
	s_cmpk_lt_u32 s19, 0x100
	global_load_lds_dwordx4 v[2:3], off
	v_and_b32_e32 v2, 15, v0
	v_and_b32_e32 v3, 48, v0
	v_lshlrev_b32_e32 v0, 2, v0
	v_lshl_or_b32 v2, v2, 6, v3
	v_and_b32_e32 v0, 32, v0
	v_bitop3_b32 v3, v2, s20, v0 bitop3:0xde
	v_bitop3_b32 v192, s21, v2, v0 bitop3:0xf6
	v_and_b32_e32 v2, 1, v9
	v_add3_u32 v0, v11, v12, v13
	v_lshlrev_b32_e32 v2, 6, v2
	v_lshl_or_b32 v0, v0, 7, v2
	s_sext_i32_i16 s11, s18
	s_cselect_b64 s[18:19], -1, 0
	s_lshl_b32 s91, s55, 7
	v_lshl_add_u32 v0, v10, 1, v0
	s_mov_b64 s[6:7], 0x8100
	v_and_b32_e32 v2, 1, v4
	s_add_u32 s20, s14, 0x5800
	v_and_b32_e32 v220, 0x780, v0
	v_lshrrev_b32_e32 v220, 1, v220
	v_and_b32_e32 v221, 64, v0
	v_lshlrev_b32_e32 v221, 4, v221
	v_and_b32_e32 v222, 48, v0
	v_and_b32_e32 v0, 0x7800, v0
	v_or3_b32 v0, v0, v220, v221
	v_or_b32_e32 v0, v0, v222
	v_lshl_add_u64 v[166:167], v[0:1], 0, s[6:7]
	v_add3_u32 v0, v6, v7, v8
	v_lshlrev_b32_e32 v2, 6, v2
	s_waitcnt vmcnt(6)
	s_addc_u32 s21, s15, 0
	v_lshl_or_b32 v0, v0, 7, v2
	v_readlane_b32 s82, v254, 16
	v_readlane_b32 s84, v254, 18
	v_readlane_b32 s94, v254, 28
	v_readlane_b32 s95, v254, 29
	s_add_u32 s22, s14, 0xb000
	v_lshl_add_u32 v0, v5, 1, v0
	s_addc_u32 s23, s15, 0
	v_and_b32_e32 v220, 0x780, v0
	v_lshrrev_b32_e32 v220, 1, v220
	v_and_b32_e32 v221, 64, v0
	v_lshlrev_b32_e32 v221, 4, v221
	v_and_b32_e32 v222, 48, v0
	v_and_b32_e32 v0, 0x7800, v0
	v_or3_b32 v0, v0, v220, v221
	v_or_b32_e32 v0, v0, v222
	v_lshl_add_u64 v[168:169], v[0:1], 0, s[6:7]
	s_mov_b32 s92, 0
	v_add_u32_e32 v193, 0, v3
	v_readlane_b32 s93, v254, 57
	v_readlane_b32 s94, v254, 58
	v_readlane_b32 s95, v254, 59
	s_movk_i32 s82, 0x5000
	s_movk_i32 s84, 0x80
	v_readlane_b32 s86, v254, 20
	v_readlane_b32 s87, v254, 21
	v_readlane_b32 s88, v254, 22
	v_readlane_b32 s89, v254, 23
	s_barrier
	s_branch .LBB0_1253

; __device__ __forceinline__ u32x4 pack8(const f32x4 a, const f32x4 b) { u32x4 w; w.x = cvt_pk_bf16(a.x, a.y); w.y = cvt_pk_bf16(a.z, a.w); w.z = cvt_pk_bf16(b.x, b.y); w.w = cvt_pk_bf16(b.z, b.w); return w; }
; __host__ __device__ __forceinline__ size_t xs_off(int row, int col) { return (size_t)(row >> 8) * (256 * D) + (size_t)(col >> 6) * (256 * 64) + (size_t)((row & 255) * 64 + (col & 63)); }
;     template <bool INF32, int M0, int M1> __device__ __forceinline__ void half(f32x4 (&acc)[2][2][4][2], int ai, int b, int row0, int col, int pn, int wc, int fr, int fq) const {
;     ...
;         for (int m = M0; m < M1; ++m) { const int row = row0 + ai * 128 + m * 16; float ss = 0.f;
; #pragma unroll
;             for (int bj = 0; bj < 2; ++bj) { const size_t o = (size_t)row * D + col + bj * 128;
;                 const f32x4 x0 = xv[m][bj][0] + gt[bj][0] * acc[ai][bj][m][0], x1 = xv[m][bj][1] + gt[bj][1] * acc[ai][bj][m][1];
;                 if (out_f32) { *(f32x4*)((float*)xout + o) = x0; *(f32x4*)((float*)xout + o + 4) = x1; }
;                 else { const f32x8_t ff = {x0.x, x0.y, x0.z, x0.w, x1.x, x1.y, x1.z, x1.w}; *(f16x8_t*)((bf16_t*)xout + o) = __builtin_convertvector(ff, f16x8_t); }
;                 ss += ((x0.x * x0.x + x0.y * x0.y) + (x0.z * x0.z + x0.w * x0.w)) + ((x1.x * x1.x + x1.y * x1.y) + (x1.z * x1.z + x1.w * x1.w));
;                 if (XS) *(u32x4*)(XS + xs_off(row0, col) + (ai * 128 + m * 16) * 64 + bj * (2 * 256 * 64)) = pack8(x0 * gs[bj][0], x1 * gs[bj][1]); }
.LBB0_1459:
	s_waitcnt vmcnt(0)
	v_cvt_f32_f16_sdwa v213, v192 dst_sel:DWORD dst_unused:UNUSED_PAD src0_sel:WORD_1
	v_cvt_f32_f16_sdwa v215, v193 dst_sel:DWORD dst_unused:UNUSED_PAD src0_sel:WORD_1
	v_cvt_f32_f16_sdwa v237, v190 dst_sel:DWORD dst_unused:UNUSED_PAD src0_sel:WORD_1
	v_cvt_f32_f16_sdwa v239, v191 dst_sel:DWORD dst_unused:UNUSED_PAD src0_sel:WORD_1
	v_cvt_f32_f16_e32 v212, v192
	v_cvt_f32_f16_e32 v214, v193
	v_cvt_f32_f16_e32 v236, v190
	v_cvt_f32_f16_e32 v238, v191
	v_ashrrev_i32_e32 v190, 6, v202
	s_ashr_i32 s10, s10, 8
	v_ashrrev_i32_e32 v191, 31, v190
	s_ashr_i32 s11, s10, 31
	v_lshlrev_b32_e32 v192, 6, v208
	v_and_b32_e32 v0, 56, v0
	s_movk_i32 s28, 0x33c0
	v_lshlrev_b64 v[190:191], 15, v[190:191]
	v_and_or_b32 v0, v192, s28, v0
	v_and_b32_e32 v244, 0x3c0, v0
	v_lshrrev_b32_e32 v244, 1, v244
	v_and_b32_e32 v245, 32, v0
	v_lshlrev_b32_e32 v245, 4, v245
	v_and_b32_e32 v0, 0x1018, v0
	v_or3_b32 v0, v0, v244, v245
	s_lshl_b64 s[10:11], s[10:11], 20
	v_pk_fma_f32 v[128:129], v[128:129], v[164:165], v[238:239]
	v_pk_fma_f32 v[126:127], v[126:127], v[162:163], v[236:237]
	v_pk_fma_f32 v[124:125], v[124:125], v[168:169], v[214:215]
	v_pk_fma_f32 v[122:123], v[122:123], v[166:167], v[212:213]
	v_lshl_add_u64 v[192:193], s[14:15], 0, v[228:229]
	v_lshl_add_u64 v[190:191], s[18:19], 0, v[190:191]
	v_cvt_pk_f16_f32 v215, v124, v125
	v_cvt_pk_f16_f32 v213, v128, v129
	v_cvt_pk_f16_f32 v214, v122, v123
	v_cvt_pk_f16_f32 v212, v126, v127
	v_lshl_add_u64 v[192:193], v[202:203], 1, v[192:193]
	v_lshl_add_u64 v[192:193], v[192:193], 0, s[100:101]
	s_and_b64 vcc, exec, s[8:9]
	v_lshl_add_u64 v[190:191], v[190:191], 0, s[10:11]
	v_lshlrev_b32_e32 v0, 1, v0
	global_store_dwordx4 v[192:193], v[212:215], off
	s_cbranch_vccnz .LBB0_1461
	s_nop 0
	v_pk_mul_f32 v[214:215], v[128:129], v[152:153]
	v_pk_mul_f32 v[212:213], v[126:127], v[150:151]
	v_pk_mul_f32 v[228:229], v[124:125], v[148:149]
	v_pk_mul_f32 v[236:237], v[122:123], v[146:147]
	v_cvt_pk_bf16_f32 v212, v212, v213
	v_cvt_pk_bf16_f32 v213, v214, v215
	s_nop 0
	v_cvt_pk_bf16_f32 v214, v236, v237
	v_cvt_pk_bf16_f32 v215, v228, v229
	v_lshl_add_u64 v[228:229], v[190:191], 0, v[0:1]
	global_store_dwordx4 v[228:229], v[212:215], off
